# gather_u: token X planes and idx prefetched two tokens ahead at the end of each token (in-order vmcnt no longer stalls row loads behind far-memory loads)
# speedup vs baseline: 1.1904x; 1.0087x over previous
; __device__ void phase_gather_u(const Params& p) {
;     ...
; #pragma unroll 1
;   for (int r = 0; r < 4; ++r) {
; #pragma unroll 1
;     for (int t = tbase; t < T_TOK; t += tstride) {
;       const u32x4 ph = xq[((size_t)t * 64 + lane) * 2], pl = xq[((size_t)t * 64 + lane) * 2 + 1];
;       const int idA = idxg[(size_t)t * 128 + lane], idB = idxg[(size_t)t * 128 + 64 + lane];
;       unsigned long long m0 = __ballot((idA >> 12) == r), m1 = __ballot((idB >> 12) == r);
.LBB0_1205:
	s_or_b64 exec, exec, s[4:5]
	v_and_b32_e32 v0, 32, v139
	v_cmp_eq_u32_e64 s[2:3], 0, v0
	v_and_b32_e32 v0, 16, v139
	v_cmp_eq_u32_e64 s[4:5], 0, v0
	v_and_b32_e32 v0, 8, v139
	s_add_u32 s10, s34, 0xc000000
	v_cmp_eq_u32_e64 s[6:7], 0, v0
	v_mov_b32_e32 v1, 0
	v_lshlrev_b32_e32 v0, 5, v138
	s_addc_u32 s11, s35, 0
	s_waitcnt lgkmcnt(0)
	v_lshl_add_u64 v[2:3], s[34:35], 0, v[0:1]
	v_lshlrev_b32_e32 v0, 2, v138
	v_lshlrev_b32_e32 v82, 3, v139
	v_writelane_b32 v250, s10, 18
	v_mbcnt_hi_u32_b32 v83, -1, v30
	v_and_b32_e32 v4, 56, v82
	v_lshl_add_u64 v[76:77], s[10:11], 0, v[0:1]
	v_lshlrev_b32_e32 v0, 4, v138
	s_waitcnt vmcnt(0)
	v_lshl_add_u64 v[72:73], s[34:35], 0, v[0:1]
	v_and_b32_e32 v0, 64, v83
	s_add_u32 s70, s34, 0x17400000
	s_mov_b64 s[8:9], 0x15400000
	v_add_u32_e32 v84, 64, v0
	v_or_b32_e32 v0, v0, v4
	s_addc_u32 s71, s35, 0
	s_mov_b32 s33, 0
	v_lshl_add_u64 v[74:75], v[2:3], 0, s[8:9]
	v_writelane_b32 v250, s11, 19
	v_cmp_gt_u32_e64 s[8:9], 8, v138
	v_cmp_eq_u32_e64 s[10:11], 1, v138
	v_cmp_eq_u32_e64 s[12:13], 2, v138
	v_cmp_eq_u32_e64 s[14:15], 3, v138
	v_cmp_eq_u32_e64 s[16:17], 4, v138
	v_cmp_eq_u32_e64 s[18:19], 5, v138
	v_cmp_eq_u32_e64 s[20:21], 6, v138
	v_cmp_eq_u32_e64 s[22:23], 7, v138
	s_movk_i32 s48, 0x3fff
	v_xor_b32_e32 v89, 32, v83
	v_xor_b32_e32 v90, 16, v83
	v_xor_b32_e32 v88, 8, v83
	v_xor_b32_e32 v87, 4, v83
	v_xor_b32_e32 v86, 2, v83
	v_xor_b32_e32 v85, 1, v83
	v_lshlrev_b32_e32 v91, 2, v0
	v_and_b32_e32 v96, 15, v138
	v_lshrrev_b32_e32 v99, 4, v138
	v_lshlrev_b32_e32 v98, 2, v138
	v_lshrrev_b32_e32 v100, 6, v139
	v_cmp_eq_u32_e64 s[8:9], 0, v96
	v_lshlrev_b32_e32 v97, 5, v96
	v_lshlrev_b32_e32 v96, 4, v96
	v_readfirstlane_b32 s60, v100
	v_readfirstlane_b32 s61, v112
	s_add_u32 s64, s34, 0x15400000
	s_addc_u32 s65, s35, 0
	s_add_u32 s62, s34, 0xc000000
	s_addc_u32 s63, s35, 0
	s_lshl_b32 s60, s60, 10
	s_and_saveexec_b64 s[38:39], s[0:1]
	s_cbranch_execz .Lgu_done
	s_mov_b32 s33, 0
	s_mov_b32 s66, 0
	s_lshl_b32 s40, s61, 9
	s_add_u32 s40, s62, s40
	s_addc_u32 s41, s63, 0
	s_lshl_b32 s46, s61, 11
	s_add_u32 s46, s64, s46
	s_addc_u32 s47, s65, 0
	global_load_dword v94, v98, s[40:41]
	global_load_dword v95, v98, s[40:41] offset:256
	global_load_dwordx4 v[168:171], v97, s[46:47]
	global_load_dwordx4 v[172:175], v97, s[46:47] offset:16
	global_load_dwordx4 v[176:179], v97, s[46:47] offset:512
	global_load_dwordx4 v[180:183], v97, s[46:47] offset:528
	global_load_dwordx4 v[184:187], v97, s[46:47] offset:1024
	global_load_dwordx4 v[188:191], v97, s[46:47] offset:1040
	global_load_dwordx4 v[192:195], v97, s[46:47] offset:1536
	global_load_dwordx4 v[196:199], v97, s[46:47] offset:1552
	s_add_i32 s37, s61, s68
	s_lshl_b32 s40, s37, 9
	s_add_u32 s40, s62, s40
	s_addc_u32 s41, s63, 0
	s_lshl_b32 s46, s37, 11
	s_add_u32 s46, s64, s46
	s_addc_u32 s47, s65, 0
	global_load_dword v232, v98, s[40:41]
	global_load_dword v233, v98, s[40:41] offset:256
	global_load_dwordx4 v[200:203], v97, s[46:47]
	global_load_dwordx4 v[204:207], v97, s[46:47] offset:16
	global_load_dwordx4 v[208:211], v97, s[46:47] offset:512
	global_load_dwordx4 v[212:215], v97, s[46:47] offset:528
	global_load_dwordx4 v[216:219], v97, s[46:47] offset:1024
	global_load_dwordx4 v[220:223], v97, s[46:47] offset:1040
	global_load_dwordx4 v[224:227], v97, s[46:47] offset:1536
	global_load_dwordx4 v[228:231], v97, s[46:47] offset:1552

; __device__ void phase_gather_u(const Params& p) {
;     ...
;     for (int t = tbase; t < T_TOK; t += tstride) {
;       const u32x4 ph = xq[((size_t)t * 64 + lane) * 2], pl = xq[((size_t)t * 64 + lane) * 2 + 1];
;       const int idA = idxg[(size_t)t * 128 + lane], idB = idxg[(size_t)t * 128 + 64 + lane];
;       unsigned long long m0 = __ballot((idA >> 12) == r), m1 = __ballot((idB >> 12) == r);
;       while (m0 | m1) {
;         int jk[16];
;         u32x4 rw[16];
;         const int nvalid = min((int)(__popcll(m0) + __popcll(m1)), 16);
;         int jfirst, efirst;
;         if (m0) { jfirst = __builtin_amdgcn_readfirstlane(__ffsll((long long)m0) - 1); efirst = __builtin_amdgcn_readlane(idA, jfirst); }
;         else { const int j1 = __builtin_amdgcn_readfirstlane(__ffsll((long long)m1) - 1); efirst = __builtin_amdgcn_readlane(idB, j1); jfirst = 64 + j1; }
; #pragma unroll
;         for (int k = 0; k < 16; ++k) {
;           int j = jfirst, e = efirst;
;           if (m0) { const int jj = __builtin_amdgcn_readfirstlane(__ffsll((long long)m0) - 1); m0 &= m0 - 1ull; j = jj; e = __builtin_amdgcn_readlane(idA, jj); }
;           else if (m1) { const int jj = __builtin_amdgcn_readfirstlane(__ffsll((long long)m1) - 1); m1 &= m1 - 1ull; j = 64 + jj; e = __builtin_amdgcn_readlane(idB, jj); }
.Lgu_tloop:
	s_lshl_b32 s37, s36, 9
	s_add_u32 s48, s70, s37
	s_addc_u32 s49, s71, 0
	s_waitcnt vmcnt(10)
	s_cmp_eq_u32 s66, 0
	s_cbranch_scc0 .Lgu_cpB
	v_mov_b64 v[0:1], v[168:169]
	v_mov_b64 v[2:3], v[170:171]
	v_mov_b64 v[4:5], v[172:173]
	v_mov_b64 v[6:7], v[174:175]
	v_mov_b64 v[8:9], v[176:177]
	v_mov_b64 v[10:11], v[178:179]
	v_mov_b64 v[12:13], v[180:181]
	v_mov_b64 v[14:15], v[182:183]
	v_mov_b64 v[16:17], v[184:185]
	v_mov_b64 v[18:19], v[186:187]
	v_mov_b64 v[20:21], v[188:189]
	v_mov_b64 v[22:23], v[190:191]
	v_mov_b64 v[24:25], v[192:193]
	v_mov_b64 v[26:27], v[194:195]
	v_mov_b64 v[28:29], v[196:197]
	v_mov_b64 v[30:31], v[198:199]
	v_mov_b32_e32 v92, v94
	v_mov_b32_e32 v93, v95
	s_branch .Lgu_cpdone
.Lgu_cpB:
	v_mov_b64 v[0:1], v[200:201]
	v_mov_b64 v[2:3], v[202:203]
	v_mov_b64 v[4:5], v[204:205]
	v_mov_b64 v[6:7], v[206:207]
	v_mov_b64 v[8:9], v[208:209]
	v_mov_b64 v[10:11], v[210:211]
	v_mov_b64 v[12:13], v[212:213]
	v_mov_b64 v[14:15], v[214:215]
	v_mov_b64 v[16:17], v[216:217]
	v_mov_b64 v[18:19], v[218:219]
	v_mov_b64 v[20:21], v[220:221]
	v_mov_b64 v[22:23], v[222:223]
	v_mov_b64 v[24:25], v[224:225]
	v_mov_b64 v[26:27], v[226:227]
	v_mov_b64 v[28:29], v[228:229]
	v_mov_b64 v[30:31], v[230:231]
	v_mov_b32_e32 v92, v232
	v_mov_b32_e32 v93, v233
.Lgu_cpdone:
	v_lshrrev_b32_e32 v103, 12, v92
	v_lshrrev_b32_e32 v104, 12, v93
	v_cmp_eq_u32_e64 s[44:45], s33, v103
	v_cmp_eq_u32_e64 s[42:43], s33, v104
	s_nop 3
	s_bcnt1_i32_b64 s59, s[44:45]
	s_bcnt1_i32_b64 s56, s[42:43]
	s_add_i32 s56, s56, s59
	s_cmp_eq_u32 s56, 0
	s_cbranch_scc1 .Lgu_tnext
	v_mbcnt_lo_u32_b32 v114, s44, 0
	v_mbcnt_hi_u32_b32 v114, s45, v114
	v_mbcnt_lo_u32_b32 v111, s42, 0
	v_mbcnt_hi_u32_b32 v111, s43, v111
	v_lshl_add_u32 v113, v92, 8, v138
	v_lshl_add_u32 v100, v114, 2, s60
	v_add_u32_e32 v111, s59, v111
	s_mov_b64 exec, s[44:45]
	ds_write_b32 v100, v113
	s_mov_b64 exec, -1
	v_add_u32_e32 v113, 64, v138
	v_lshl_add_u32 v100, v111, 2, s60
	v_lshl_add_u32 v113, v93, 8, v113
	s_mov_b64 exec, s[42:43]
	ds_write_b32 v100, v113
	s_mov_b64 exec, -1
	s_add_i32 s57, s56, 3
	s_lshr_b32 s57, s57, 2
	v_lshl_add_u32 v101, v99, 2, s60
	v_mov_b32_e32 v102, v99
	s_mov_b32 s58, 0
	ds_read_b32 v115, v101
	v_add_u32_e32 v101, 16, v101
	s_waitcnt lgkmcnt(0)
	v_mov_b32_e32 v103, v115
	ds_read_b32 v115, v101
	v_cmp_gt_u32_e64 s[50:51], s56, v102
	v_add_u32_e32 v101, 16, v101
	v_add_u32_e32 v102, 4, v102
	s_nop 0
	v_cndmask_b32_e64 v103, 0, v103, s[50:51]
	v_and_b32_e32 v104, 0xffffff00, v103
	v_and_b32_e32 v105, 0xff, v103
	v_lshl_add_u32 v104, v104, 2, v96
	v_lshlrev_b32_e32 v105, 2, v105
	s_and_b64 s[50:51], s[50:51], s[8:9]
	global_load_dwordx4 v[32:35], v104, s[34:35]
	global_load_dwordx4 v[36:39], v104, s[34:35] offset:256
	global_load_dwordx4 v[40:43], v104, s[34:35] offset:512
	global_load_dwordx4 v[44:47], v104, s[34:35] offset:768
	s_waitcnt lgkmcnt(0)
	v_mov_b32_e32 v103, v115
	ds_read_b32 v115, v101
	v_cmp_gt_u32_e64 s[52:53], s56, v102
	v_add_u32_e32 v101, 16, v101
	v_add_u32_e32 v102, 4, v102
	s_nop 0
	v_cndmask_b32_e64 v103, 0, v103, s[52:53]
	v_and_b32_e32 v104, 0xffffff00, v103
	v_and_b32_e32 v106, 0xff, v103
	v_lshl_add_u32 v104, v104, 2, v96
	v_lshlrev_b32_e32 v106, 2, v106
	s_and_b64 s[52:53], s[52:53], s[8:9]
	global_load_dwordx4 v[48:51], v104, s[34:35]
	global_load_dwordx4 v[52:55], v104, s[34:35] offset:256
	global_load_dwordx4 v[56:59], v104, s[34:35] offset:512
	global_load_dwordx4 v[60:63], v104, s[34:35] offset:768

; __device__ void phase_gather_u(const Params& p) {
;     ...
;   for (int r = 0; r < 4; ++r) {
; #pragma unroll 1
;     for (int t = tbase; t < T_TOK; t += tstride) {
;       const u32x4 ph = xq[((size_t)t * 64 + lane) * 2], pl = xq[((size_t)t * 64 + lane) * 2 + 1];
;       const int idA = idxg[(size_t)t * 128 + lane], idB = idxg[(size_t)t * 128 + 64 + lane];
;       unsigned long long m0 = __ballot((idA >> 12) == r), m1 = __ballot((idB >> 12) == r);
.Lgu_tnext:
	s_lshl_b32 s37, s68, 1
	s_add_i32 s37, s37, s36
	s_sub_i32 s40, s37, 0x4000
	s_cmp_gt_i32 s37, 0x3fff
	s_cselect_b32 s37, s40, s37
	s_cmp_eq_u32 s66, 0
	s_cbranch_scc0 .Lgu_pfB
	s_lshl_b32 s40, s37, 9
	s_add_u32 s40, s62, s40
	s_addc_u32 s41, s63, 0
	s_lshl_b32 s46, s37, 11
	s_add_u32 s46, s64, s46
	s_addc_u32 s47, s65, 0
	global_load_dword v94, v98, s[40:41]
	global_load_dword v95, v98, s[40:41] offset:256
	global_load_dwordx4 v[168:171], v97, s[46:47]
	global_load_dwordx4 v[172:175], v97, s[46:47] offset:16
	global_load_dwordx4 v[176:179], v97, s[46:47] offset:512
	global_load_dwordx4 v[180:183], v97, s[46:47] offset:528
	global_load_dwordx4 v[184:187], v97, s[46:47] offset:1024
	global_load_dwordx4 v[188:191], v97, s[46:47] offset:1040
	global_load_dwordx4 v[192:195], v97, s[46:47] offset:1536
	global_load_dwordx4 v[196:199], v97, s[46:47] offset:1552
	s_branch .Lgu_pfdone
.Lgu_pfB:
	s_lshl_b32 s40, s37, 9
	s_add_u32 s40, s62, s40
	s_addc_u32 s41, s63, 0
	s_lshl_b32 s46, s37, 11
	s_add_u32 s46, s64, s46
	s_addc_u32 s47, s65, 0
	global_load_dword v232, v98, s[40:41]
	global_load_dword v233, v98, s[40:41] offset:256
	global_load_dwordx4 v[200:203], v97, s[46:47]
	global_load_dwordx4 v[204:207], v97, s[46:47] offset:16
	global_load_dwordx4 v[208:211], v97, s[46:47] offset:512
	global_load_dwordx4 v[212:215], v97, s[46:47] offset:528
	global_load_dwordx4 v[216:219], v97, s[46:47] offset:1024
	global_load_dwordx4 v[220:223], v97, s[46:47] offset:1040
	global_load_dwordx4 v[224:227], v97, s[46:47] offset:1536
	global_load_dwordx4 v[228:231], v97, s[46:47] offset:1552
.Lgu_pfdone:
	s_xor_b32 s66, s66, 1
	s_add_i32 s36, s36, s68
	s_cmp_le_i32 s36, 0x3fff
	s_cbranch_scc1 .Lgu_tloop
	s_add_i32 s33, s33, 1
	s_cmp_lt_u32 s33, 4
	s_cbranch_scc1 .Lgu_rloop
